# staging waves: two running-sum slots addressed by buffer parity, lower-wave totals read through per-wave addresses (zero row when unused), y base pointer advanced on the scalar side; relaxed scan-wave
# baseline (speedup 1.0000x reference)
.Lsc_item:
	v_lshlrev_b32_e32 v164, 2, v0
	v_add_u32_e32 v164, 139776, v164
	v_xor_b32_e32 v164, 16, v164
	ds_write_b32 v164, v169
	v_and_b32_e32 v163, 3, v0
	v_lshlrev_b32_e32 v163, 2, v163
	v_add_u32_e32 v163, 139808, v163
	ds_write_b32 v163, v169
	v_and_b32_e32 v162, 1, v0
	v_lshlrev_b32_e32 v162, 10, v162
	v_and_b32_e32 v163, 63, v173
	v_lshl_add_u32 v162, v163, 2, v162
	v_add_u32_e32 v162, 141888, v162
	ds_write_b32 v162, v169
	s_waitcnt lgkmcnt(0)
	s_barrier
	s_cmp_ge_u32 s7, 4
	s_cbranch_scc1 .Lsc_G
	v_lshlrev_b32_e32 v27, 2, v173
	v_and_b32_e32 v27, 60, v27
	v_lshlrev_b32_e32 v7, 2, v0
	v_bfe_u32 v1, v173, 4, 2
	v_or_b32_e32 v37, v7, v1
	v_lshlrev_b32_e32 v37, 6, v37
	v_and_b32_e32 v36, 15, v173
	v_lshl_add_u32 v37, v36, 2, v37
	v_add_u32_e32 v37, 74240, v37
	v_and_b32_e32 v34, 15, v173
	v_lshlrev_b32_e32 v34, 4, v34
	v_or_b32_e32 v35, v7, v1
	v_mul_u32_u24_e32 v35, 144, v35
	v_add_u32_e32 v35, 69632, v35
	v_mov_b32_e32 v8, 0
	v_mov_b32_e32 v9, 0
	v_mov_b32_e32 v10, 0
	v_mov_b32_e32 v11, 0
	v_add_u32_e32 v48, 34816, v34
	v_add_u32_e32 v49, 2304, v35
	v_add_u32_e32 v50, 32768, v37
	v_mov_b32_e32 v51, 0
	v_mov_b32_e32 v52, 139776
	v_mov_b32_e32 v53, v164
	s_mov_b32 s6, 0
	s_mov_b32 s55, 0x100000

.Lsc_G:
	v_add_u32_e32 v1, 0xffffff00, v173
	v_lshrrev_b32_e32 v2, 3, v1
	v_and_b32_e32 v3, 7, v1
	s_and_b32 s8, s4, 7
	s_bfe_u32 s10, s4, 0x20003
	s_lshr_b32 s11, s4, 7
	s_bfe_u32 s9, s4, 0x20005
	s_lshl_b32 s9, s9, 13
	v_readlane_b32 s50, v242, 0
	v_readlane_b32 s51, v242, 1
	v_readlane_b32 s16, v242, 62
	s_load_dwordx4 s[12:15], s[50:51], 0x68
	s_add_u32 s36, s90, 0x5e00000
	s_addc_u32 s37, s91, 0
	s_add_u32 s38, s90, 0x7e00000
	s_addc_u32 s39, s91, 0
	s_add_u32 s44, s90, 0x9e00000
	s_addc_u32 s45, s91, 0
	s_add_u32 s46, s90, 0x1c00000
	s_addc_u32 s47, s91, 0
	s_lshl_b32 s68, s11, 25
	s_add_u32 s69, s68, 0x13e00000
	s_add_u32 s40, s90, s69
	s_addc_u32 s41, s91, 0
	s_add_u32 s69, s68, 0x17e00000
	s_add_u32 s42, s90, s69
	s_addc_u32 s43, s91, 0
	s_lshl_b32 s68, s11, 26
	s_add_u32 s68, s68, 0xbe00000
	s_add_u32 s48, s90, s68
	s_addc_u32 s49, s91, 0
	s_cmp_eq_u32 s11, 0
	s_mov_b32 s54, 0x8000
	s_movk_i32 s55, 0x400
	s_mov_b32 s64, 0x10000
	s_cselect_b32 s54, s54, 0xffff8000
	s_cselect_b32 s55, s55, 0xfffffc00
	s_cselect_b32 s64, s64, 0xffff0000
	s_cselect_b64 vcc, -1, 0
	s_ashr_i32 s50, s64, 31
	v_sub_u32_e32 v4, 0x1fff, v2
	s_nop 3
	v_cndmask_b32_e32 v4, v4, v2, vcc
	v_add_u32_e32 v4, s9, v4
	s_lshl_b32 s68, s8, 7
	v_lshlrev_b32_e32 v5, 10, v4
	v_lshl_add_u32 v5, v3, 3, v5
	v_add_u32_e32 v5, s68, v5
	s_lshl_b32 s69, s8, 2
	v_lshlrev_b32_e32 v6, 5, v4
	v_add_u32_e32 v6, s69, v6
	s_lshl_b32 s69, s10, 5
	s_add_i32 s69, s69, s68
	v_lshlrev_b32_e32 v9, 10, v4
	v_lshl_add_u32 v9, v3, 2, v9
	v_add_u32_e32 v9, s69, v9
	s_lshl_b32 s65, s69, 1
	v_mul_u32_u24_e32 v8, 1024, v2
	v_lshl_add_u32 v8, v3, 4, v8
	v_add_u32_e32 v138, 512, v8
	v_add_u32_e32 v140, 35328, v8
	v_add_u32_e32 v152, -4, v0
	v_mul_u32_u24_e32 v152, 4608, v152
	v_add_u32_e32 v152, 143936, v152
	v_and_b32_e32 v156, 7, v2
	v_lshlrev_b32_e32 v153, 8, v156
	v_lshl_add_u32 v153, v3, 4, v153
	v_add_u32_e32 v153, v152, v153
	v_and_b32_e32 v154, 63, v1
	v_lshl_add_u32 v154, v154, 2, v152
	v_add_u32_e32 v155, 2048, v154
	v_add_u32_e32 v139, -1, v2
	v_mul_u32_u24_e32 v139, 1024, v139
	v_lshl_add_u32 v139, v3, 4, v139
	v_add_u32_e32 v141, 35328, v139
	v_add_u32_e32 v139, 512, v139
	v_cmp_eq_u32_e32 vcc, 0, v2
	s_nop 1
	v_cndmask_b32_e32 v139, v139, v152, vcc
	v_cndmask_b32_e32 v141, v141, v152, vcc
	v_lshrrev_b32_e32 v158, 3, v2
	v_lshlrev_b32_e32 v158, 8, v158
	v_lshl_add_u32 v158, v3, 4, v158
	v_and_b32_e32 v159, 63, v1
	v_lshlrev_b32_e32 v159, 2, v159
	v_add_u32_e32 v106, -4, v0
	v_lshl_add_u32 v159, v106, 8, v159
	v_add_u32_e32 v159, 33792, v159
	v_add_u32_e32 v106, -4, v0
	v_lshlrev_b32_e32 v162, 2, v106
	v_add_u32_e32 v162, 139808, v162
	v_mov_b32_e32 v163, 139808
	v_and_b32_e32 v181, 63, v1
	v_lshlrev_b32_e32 v181, 2, v181
	v_add_u32_e32 v181, 139840, v181
	v_lshl_add_u32 v180, v106, 8, v181
	v_add_u32_e32 v198, 2048, v181
	v_cmp_gt_u32_e32 vcc, v106, v169
	s_nop 1
	v_add_u32_e32 v174, 0, v181
	v_cndmask_b32_e32 v174, v198, v174, vcc
	v_mov_b32_e32 v177, 0x7fffffff
	v_cndmask_b32_e32 v177, v177, v169, vcc
	v_cmp_lt_u32_e32 vcc, 1, v106
	s_nop 1
	v_add_u32_e32 v175, 256, v181
	v_cndmask_b32_e32 v175, v198, v175, vcc
	v_mov_b32_e32 v178, 0x7fffffff
	v_cndmask_b32_e32 v178, v178, v169, vcc
	v_cmp_lt_u32_e32 vcc, 2, v106
	s_nop 1
	v_add_u32_e32 v176, 512, v181
	v_cndmask_b32_e32 v176, v198, v176, vcc
	v_mov_b32_e32 v179, 0x7fffffff
	v_cndmask_b32_e32 v179, v179, v169, vcc
	v_add_u32_e32 v158, 32768, v158
	v_mul_u32_u24_e32 v142, 288, v3
	v_lshl_add_u32 v142, v2, 2, v142
	v_add_u32_e32 v143, 71936, v142
	v_add_u32_e32 v142, 69632, v142
	s_lshl_b32 s69, s8, 6
	s_add_i32 s69, s69, s16
	v_lshl_add_u32 v106, v3, 2, s69
	v_lshlrev_b32_e32 v106, 2, v106
	s_waitcnt lgkmcnt(0)
	global_load_dwordx4 v[12:15], v106, s[12:13]
	global_load_dwordx4 v[16:19], v106, s[12:13] offset:128
	global_load_dwordx4 v[20:23], v106, s[14:15]
	global_load_dwordx4 v[24:27], v106, s[14:15] offset:128
	global_load_dwordx2 v[28:29], v5, s[36:37]
	global_load_dwordx2 v[30:31], v5, s[36:37] offset:64
	global_load_dwordx2 v[32:33], v5, s[38:39]
	global_load_dwordx2 v[34:35], v5, s[38:39] offset:64
	global_load_dwordx2 v[36:37], v5, s[40:41]
	global_load_dwordx2 v[38:39], v5, s[40:41] offset:64
	global_load_dwordx2 v[40:41], v5, s[42:43]
	global_load_dwordx2 v[42:43], v5, s[42:43] offset:64
	global_load_dword v44, v6, s[46:47]
	global_load_dword v45, v9, s[44:45]
	v_add_u32_e32 v5, s54, v5
	v_add_u32_e32 v6, s55, v6
	v_add_u32_e32 v9, s54, v9
	global_load_dwordx2 v[46:47], v5, s[36:37]
	global_load_dwordx2 v[48:49], v5, s[36:37] offset:64
	global_load_dwordx2 v[50:51], v5, s[38:39]
	global_load_dwordx2 v[52:53], v5, s[38:39] offset:64
	global_load_dwordx2 v[54:55], v5, s[40:41]
	global_load_dwordx2 v[56:57], v5, s[40:41] offset:64
	global_load_dwordx2 v[58:59], v5, s[42:43]
	global_load_dwordx2 v[60:61], v5, s[42:43] offset:64
	global_load_dword v62, v6, s[46:47]
	global_load_dword v63, v9, s[44:45]
	v_add_u32_e32 v5, s54, v5
	v_add_u32_e32 v6, s55, v6
	v_add_u32_e32 v9, s54, v9
	v_and_b32_e32 v166, 15, v1
	v_lshrrev_b32_e32 v167, 4, v1
	v_sub_u32_e32 v4, 0x1fff, v167
	s_cmp_eq_u32 s11, 0
	s_cselect_b64 vcc, -1, 0
	s_nop 3
	v_cndmask_b32_e32 v4, v4, v167, vcc
	v_add_u32_e32 v4, s9, v4
	v_lshlrev_b32_e32 v7, 11, v4
	v_lshl_add_u32 v7, v166, 2, v7
	v_add_u32_e32 v7, s65, v7
	s_ashr_i32 s65, s64, 1
	v_add_u32_e32 v165, s65, v7
	v_lshlrev_b32_e32 v11, 10, v167
	v_lshl_add_u32 v11, v166, 6, v11
	v_add_u32_e32 v11, 74240, v11
	v_lshrrev_b32_e32 v166, 2, v166
	v_add_u32_e32 v2, 0, v166
	v_and_b32_e32 v2, 3, v2
	v_lshl_add_u32 v2, v2, 4, v11
	v_add_u32_e32 v3, 1, v166
	v_and_b32_e32 v3, 3, v3
	v_lshl_add_u32 v3, v3, 4, v11
	v_add_u32_e32 v4, 2, v166
	v_and_b32_e32 v4, 3, v4
	v_lshl_add_u32 v4, v4, 4, v11
	v_add_u32_e32 v10, 3, v166
	v_and_b32_e32 v10, 3, v10
	v_lshl_add_u32 v10, v10, 4, v11
	s_waitcnt vmcnt(20)
	v_pk_add_f32 v[190:191], v[20:21], 1.0 op_sel_hi:[1,0] neg_lo:[1,0] neg_hi:[1,0]
	v_pk_add_f32 v[192:193], v[22:23], 1.0 op_sel_hi:[1,0] neg_lo:[1,0] neg_hi:[1,0]
	v_pk_add_f32 v[194:195], v[24:25], 1.0 op_sel_hi:[1,0] neg_lo:[1,0] neg_hi:[1,0]
	v_pk_add_f32 v[196:197], v[26:27], 1.0 op_sel_hi:[1,0] neg_lo:[1,0] neg_hi:[1,0]
	v_cmp_eq_u32_e64 s[12:13], 0, v156
	s_mov_b32 s14, 0x3fb8aa3b
	s_mov_b32 s6, 0
	v_mov_b32_e32 v144, 139792
	v_mov_b32_e32 v145, v164
	v_mov_b32_e32 v146, 0
	s_waitcnt vmcnt(10)
	v_lshlrev_b32_e32 v64, 16, v36
	v_and_b32_e32 v65, 0xffff0000, v36
	v_lshlrev_b32_e32 v66, 16, v37
	v_and_b32_e32 v67, 0xffff0000, v37
	v_lshlrev_b32_e32 v68, 16, v38
	v_and_b32_e32 v69, 0xffff0000, v38
	v_lshlrev_b32_e32 v70, 16, v39
	v_and_b32_e32 v71, 0xffff0000, v39
	ds_write_b128 v153, v[64:67]
	ds_write_b128 v153, v[68:71] offset:128
	s_waitcnt lgkmcnt(0)
	ds_read_b32 v124, v154 offset:0
	ds_read_b32 v125, v154 offset:256
	ds_read_b32 v126, v154 offset:512
	ds_read_b32 v127, v154 offset:768
	ds_read_b32 v128, v154 offset:1024
	ds_read_b32 v129, v154 offset:1280
	ds_read_b32 v130, v154 offset:1536
	ds_read_b32 v131, v154 offset:1792
	v_lshlrev_b32_e32 v108, 16, v32
	v_and_b32_e32 v109, 0xffff0000, v32
	v_lshlrev_b32_e32 v110, 16, v40
	v_and_b32_e32 v111, 0xffff0000, v40
	v_lshlrev_b32_e32 v96, 16, v28
	v_and_b32_e32 v97, 0xffff0000, v28
	v_pk_mul_f32 v[114:115], v[12:13], v[108:109]
	v_pk_fma_f32 v[112:113], v[20:21], v[110:111], v[190:191]
	v_pk_mul_f32 v[88:89], v[44:45], v[114:115] op_sel_hi:[0,1]
	v_pk_mul_f32 v[72:73], v[112:113], v[108:109]
	v_pk_mul_f32 v[80:81], v[88:89], v[110:111]
	v_lshlrev_b32_e32 v108, 16, v33
	v_and_b32_e32 v109, 0xffff0000, v33
	v_lshlrev_b32_e32 v110, 16, v41
	v_and_b32_e32 v111, 0xffff0000, v41
	v_lshlrev_b32_e32 v98, 16, v29
	v_and_b32_e32 v99, 0xffff0000, v29
	v_pk_mul_f32 v[114:115], v[14:15], v[108:109]
	v_pk_fma_f32 v[112:113], v[22:23], v[110:111], v[192:193]
	v_pk_mul_f32 v[90:91], v[44:45], v[114:115] op_sel_hi:[0,1]
	v_pk_mul_f32 v[74:75], v[112:113], v[108:109]
	v_pk_mul_f32 v[82:83], v[90:91], v[110:111]
	v_lshlrev_b32_e32 v108, 16, v34
	v_and_b32_e32 v109, 0xffff0000, v34
	v_lshlrev_b32_e32 v110, 16, v42
	v_and_b32_e32 v111, 0xffff0000, v42
	v_lshlrev_b32_e32 v100, 16, v30
	v_and_b32_e32 v101, 0xffff0000, v30
	v_pk_mul_f32 v[114:115], v[16:17], v[108:109]
	v_pk_fma_f32 v[112:113], v[24:25], v[110:111], v[194:195]
	v_pk_mul_f32 v[92:93], v[44:45], v[114:115] op_sel_hi:[0,1]
	v_pk_mul_f32 v[76:77], v[112:113], v[108:109]
	v_pk_mul_f32 v[84:85], v[92:93], v[110:111]
	v_lshlrev_b32_e32 v108, 16, v35
	v_and_b32_e32 v109, 0xffff0000, v35
	v_lshlrev_b32_e32 v110, 16, v43
	v_and_b32_e32 v111, 0xffff0000, v43
	v_lshlrev_b32_e32 v102, 16, v31
	v_and_b32_e32 v103, 0xffff0000, v31
	v_pk_mul_f32 v[114:115], v[18:19], v[108:109]
	v_pk_fma_f32 v[112:113], v[26:27], v[110:111], v[196:197]
	v_pk_mul_f32 v[94:95], v[44:45], v[114:115] op_sel_hi:[0,1]
	v_pk_mul_f32 v[78:79], v[112:113], v[108:109]
	v_pk_mul_f32 v[86:87], v[94:95], v[110:111]
	v_lshlrev_b32_e32 v104, 16, v45
	v_and_b32_e32 v105, 0xffff0000, v45
	s_waitcnt lgkmcnt(0)
	v_add_f32_e32 v125, v124, v125
	v_add_f32_e32 v126, v125, v126
	v_add_f32_e32 v127, v126, v127
	v_add_f32_e32 v128, v127, v128
	v_add_f32_e32 v129, v128, v129
	v_add_f32_e32 v130, v129, v130
	v_add_f32_e32 v131, v130, v131
	v_mul_f32_e32 v189, 0x3fb8aa3b, v131
	ds_write_b32 v180, v189 offset:0
	v_add_u32_e32 v184, 1, v146
	s_waitcnt lgkmcnt(0)
	ds_write_b32 v162, v184
	s_add_u32 s73, s6, 1
	s_mov_b32 s69, 0x100000

.Lsc_gf_go1:
	ds_read_b32 v185, v174 offset:0
	ds_read_b32 v186, v175 offset:0
	ds_read_b32 v187, v176 offset:0
	s_waitcnt lgkmcnt(0)
	v_add_f32_e32 v185, v185, v186
	v_add_f32_e32 v185, v185, v187
	v_fma_f32 v124, v124, s14, v185
	v_fma_f32 v125, v125, s14, v185
	v_fma_f32 v126, v126, s14, v185
	v_fma_f32 v127, v127, s14, v185
	v_fma_f32 v128, v128, s14, v185
	v_fma_f32 v129, v129, s14, v185
	v_fma_f32 v130, v130, s14, v185
	v_fma_f32 v131, v131, s14, v185
	v_exp_f32_e64 v188, -v185
	v_exp_f32_e64 v124, -v124
	v_exp_f32_e64 v125, -v125
	v_exp_f32_e64 v126, -v126
	v_exp_f32_e64 v127, -v127
	v_exp_f32_e64 v128, -v128
	v_exp_f32_e64 v129, -v129
	v_exp_f32_e64 v130, -v130
	v_exp_f32_e64 v131, -v131
	s_nop 0
	ds_write_b32 v155, v188
	ds_write_b32 v155, v124 offset:256
	ds_write_b32 v155, v125 offset:512
	ds_write_b32 v155, v126 offset:768
	ds_write_b32 v155, v127 offset:1024
	ds_write_b32 v155, v128 offset:1280
	ds_write_b32 v155, v129 offset:1536
	ds_write_b32 v155, v130 offset:1792
	ds_write_b32 v155, v131 offset:2048
	v_mov_b32_e32 v161, v131
	s_waitcnt lgkmcnt(0)
	ds_read_b128 v[64:67], v153 offset:2048
	ds_read_b128 v[68:71], v153 offset:2176
	ds_read_b128 v[116:119], v153 offset:2304
	ds_read_b128 v[120:123], v153 offset:2432
	s_waitcnt lgkmcnt(0)
	v_rcp_f32_e32 v124, v116
	v_rcp_f32_e32 v125, v117
	v_rcp_f32_e32 v126, v118
	v_rcp_f32_e32 v127, v119
	v_rcp_f32_e32 v128, v120
	v_rcp_f32_e32 v129, v121
	v_rcp_f32_e32 v130, v122
	v_rcp_f32_e32 v131, v123
	s_nop 1
	v_pk_mul_f32 v[72:73], v[72:73], v[124:125]
	v_pk_mul_f32 v[80:81], v[80:81], v[124:125]
	v_pk_mul_f32 v[88:89], v[88:89], v[64:65]
	v_pk_mul_f32 v[96:97], v[96:97], v[116:117]
	v_pk_mul_f32 v[74:75], v[74:75], v[126:127]
	v_pk_mul_f32 v[82:83], v[82:83], v[126:127]
	v_pk_mul_f32 v[90:91], v[90:91], v[66:67]
	v_pk_mul_f32 v[98:99], v[98:99], v[118:119]
	v_pk_mul_f32 v[76:77], v[76:77], v[128:129]
	v_pk_mul_f32 v[84:85], v[84:85], v[128:129]
	v_pk_mul_f32 v[92:93], v[92:93], v[68:69]
	v_pk_mul_f32 v[100:101], v[100:101], v[120:121]
	v_pk_mul_f32 v[78:79], v[78:79], v[130:131]
	v_pk_mul_f32 v[86:87], v[86:87], v[130:131]
	v_pk_mul_f32 v[94:95], v[94:95], v[70:71]
	v_pk_mul_f32 v[102:103], v[102:103], v[122:123]
	global_load_dwordx2 v[28:29], v5, s[36:37]
	global_load_dwordx2 v[30:31], v5, s[36:37] offset:64
	global_load_dwordx2 v[32:33], v5, s[38:39]
	global_load_dwordx2 v[34:35], v5, s[38:39] offset:64
	global_load_dwordx2 v[36:37], v5, s[40:41]
	global_load_dwordx2 v[38:39], v5, s[40:41] offset:64
	global_load_dwordx2 v[40:41], v5, s[42:43]
	global_load_dwordx2 v[42:43], v5, s[42:43] offset:64
	global_load_dword v44, v6, s[46:47]
	global_load_dword v45, v9, s[44:45]
	v_add_u32_e32 v5, s54, v5
	v_add_u32_e32 v6, s55, v6
	v_add_u32_e32 v9, s54, v9
	ds_write_b32 v159, v161 offset:0
	ds_write_b128 v8, v[72:75] offset:0
	s_sleep 1
	ds_write_b128 v8, v[76:79] offset:128
	ds_write_b128 v8, v[80:83] offset:256
	s_sleep 1
	ds_write_b128 v8, v[84:87] offset:384
	ds_write2_b32 v138, v96, v97 offset0:1 offset1:3
	s_sleep 1
	ds_write2_b32 v139, v88, v89 offset0:0 offset1:2
	ds_write2_b32 v138, v98, v99 offset0:65 offset1:67
	s_sleep 1
	ds_write2_b32 v139, v90, v91 offset0:64 offset1:66
	ds_write2_b32 v138, v100, v101 offset0:33 offset1:35
	s_sleep 1
	ds_write2_b32 v139, v92, v93 offset0:32 offset1:34
	ds_write2_b32 v138, v102, v103 offset0:97 offset1:99
	s_sleep 1
	ds_write2_b32 v139, v94, v95 offset0:96 offset1:98
	ds_write2_b32 v142, v104, v105 offset1:36
	s_sleep 1
	s_cmp_lg_u32 s7, 4
	s_cbranch_scc1 .Lsc_nokb1
	s_and_saveexec_b64 s[68:69], s[12:13]
	ds_write_b128 v158, v[88:91] offset:0
	ds_write_b128 v158, v[92:95] offset:128
	s_mov_b64 exec, s[68:69]
.Lsc_nokb1:
	s_add_i32 s6, s6, 1
	v_add_u32_e32 v146, 1, v146
	s_waitcnt lgkmcnt(0)
	ds_write_b32 v145, v146
	s_waitcnt vmcnt(10)
	v_lshlrev_b32_e32 v64, 16, v54
	v_and_b32_e32 v65, 0xffff0000, v54
	v_lshlrev_b32_e32 v66, 16, v55
	v_and_b32_e32 v67, 0xffff0000, v55
	v_lshlrev_b32_e32 v68, 16, v56
	v_and_b32_e32 v69, 0xffff0000, v56
	v_lshlrev_b32_e32 v70, 16, v57
	v_and_b32_e32 v71, 0xffff0000, v57
	ds_write_b128 v153, v[64:67]
	ds_write_b128 v153, v[68:71] offset:128
	s_waitcnt lgkmcnt(0)
	ds_read_b32 v124, v154 offset:0
	ds_read_b32 v125, v154 offset:256
	ds_read_b32 v126, v154 offset:512
	ds_read_b32 v127, v154 offset:768
	ds_read_b32 v128, v154 offset:1024
	ds_read_b32 v129, v154 offset:1280
	ds_read_b32 v130, v154 offset:1536
	ds_read_b32 v131, v154 offset:1792
	v_lshlrev_b32_e32 v108, 16, v50
	v_and_b32_e32 v109, 0xffff0000, v50
	v_lshlrev_b32_e32 v110, 16, v58
	v_and_b32_e32 v111, 0xffff0000, v58
	v_lshlrev_b32_e32 v96, 16, v46
	v_and_b32_e32 v97, 0xffff0000, v46
	v_pk_mul_f32 v[114:115], v[12:13], v[108:109]
	v_pk_fma_f32 v[112:113], v[20:21], v[110:111], v[190:191]
	v_pk_mul_f32 v[88:89], v[62:63], v[114:115] op_sel_hi:[0,1]
	v_pk_mul_f32 v[72:73], v[112:113], v[108:109]
	v_pk_mul_f32 v[80:81], v[88:89], v[110:111]
	v_lshlrev_b32_e32 v108, 16, v51
	v_and_b32_e32 v109, 0xffff0000, v51
	v_lshlrev_b32_e32 v110, 16, v59
	v_and_b32_e32 v111, 0xffff0000, v59
	v_lshlrev_b32_e32 v98, 16, v47
	v_and_b32_e32 v99, 0xffff0000, v47
	v_pk_mul_f32 v[114:115], v[14:15], v[108:109]
	v_pk_fma_f32 v[112:113], v[22:23], v[110:111], v[192:193]
	v_pk_mul_f32 v[90:91], v[62:63], v[114:115] op_sel_hi:[0,1]
	v_pk_mul_f32 v[74:75], v[112:113], v[108:109]
	v_pk_mul_f32 v[82:83], v[90:91], v[110:111]
	v_lshlrev_b32_e32 v108, 16, v52
	v_and_b32_e32 v109, 0xffff0000, v52
	v_lshlrev_b32_e32 v110, 16, v60
	v_and_b32_e32 v111, 0xffff0000, v60
	v_lshlrev_b32_e32 v100, 16, v48
	v_and_b32_e32 v101, 0xffff0000, v48
	v_pk_mul_f32 v[114:115], v[16:17], v[108:109]
	v_pk_fma_f32 v[112:113], v[24:25], v[110:111], v[194:195]
	v_pk_mul_f32 v[92:93], v[62:63], v[114:115] op_sel_hi:[0,1]
	v_pk_mul_f32 v[76:77], v[112:113], v[108:109]
	v_pk_mul_f32 v[84:85], v[92:93], v[110:111]
	v_lshlrev_b32_e32 v108, 16, v53
	v_and_b32_e32 v109, 0xffff0000, v53
	v_lshlrev_b32_e32 v110, 16, v61
	v_and_b32_e32 v111, 0xffff0000, v61
	v_lshlrev_b32_e32 v102, 16, v49
	v_and_b32_e32 v103, 0xffff0000, v49
	v_pk_mul_f32 v[114:115], v[18:19], v[108:109]
	v_pk_fma_f32 v[112:113], v[26:27], v[110:111], v[196:197]
	v_pk_mul_f32 v[94:95], v[62:63], v[114:115] op_sel_hi:[0,1]
	v_pk_mul_f32 v[78:79], v[112:113], v[108:109]
	v_pk_mul_f32 v[86:87], v[94:95], v[110:111]
	v_lshlrev_b32_e32 v104, 16, v63
	v_and_b32_e32 v105, 0xffff0000, v63
	s_waitcnt lgkmcnt(0)
	v_add_f32_e32 v125, v124, v125
	v_add_f32_e32 v126, v125, v126
	v_add_f32_e32 v127, v126, v127
	v_add_f32_e32 v128, v127, v128
	v_add_f32_e32 v129, v128, v129
	v_add_f32_e32 v130, v129, v130
	v_add_f32_e32 v131, v130, v131
	v_mul_f32_e32 v189, 0x3fb8aa3b, v131
	ds_write_b32 v180, v189 offset:1024
	v_add_u32_e32 v184, 1, v146
	s_waitcnt lgkmcnt(0)
	ds_write_b32 v162, v184
	s_add_u32 s73, s6, 1
	s_mov_b32 s69, 0x100000

.Lsc_gf_go2:
	ds_read_b32 v185, v174 offset:1024
	ds_read_b32 v186, v175 offset:1024
	ds_read_b32 v187, v176 offset:1024
	s_waitcnt lgkmcnt(0)
	v_add_f32_e32 v185, v185, v186
	v_add_f32_e32 v185, v185, v187
	v_fma_f32 v124, v124, s14, v185
	v_fma_f32 v125, v125, s14, v185
	v_fma_f32 v126, v126, s14, v185
	v_fma_f32 v127, v127, s14, v185
	v_fma_f32 v128, v128, s14, v185
	v_fma_f32 v129, v129, s14, v185
	v_fma_f32 v130, v130, s14, v185
	v_fma_f32 v131, v131, s14, v185
	v_exp_f32_e64 v188, -v185
	v_exp_f32_e64 v124, -v124
	v_exp_f32_e64 v125, -v125
	v_exp_f32_e64 v126, -v126
	v_exp_f32_e64 v127, -v127
	v_exp_f32_e64 v128, -v128
	v_exp_f32_e64 v129, -v129
	v_exp_f32_e64 v130, -v130
	v_exp_f32_e64 v131, -v131
	s_nop 0
	ds_write_b32 v155, v188
	ds_write_b32 v155, v124 offset:256
	ds_write_b32 v155, v125 offset:512
	ds_write_b32 v155, v126 offset:768
	ds_write_b32 v155, v127 offset:1024
	ds_write_b32 v155, v128 offset:1280
	ds_write_b32 v155, v129 offset:1536
	ds_write_b32 v155, v130 offset:1792
	ds_write_b32 v155, v131 offset:2048
	v_mov_b32_e32 v161, v131
	s_waitcnt lgkmcnt(0)
	ds_read_b128 v[64:67], v153 offset:2048
	ds_read_b128 v[68:71], v153 offset:2176
	ds_read_b128 v[116:119], v153 offset:2304
	ds_read_b128 v[120:123], v153 offset:2432
	s_waitcnt lgkmcnt(0)
	v_rcp_f32_e32 v124, v116
	v_rcp_f32_e32 v125, v117
	v_rcp_f32_e32 v126, v118
	v_rcp_f32_e32 v127, v119
	v_rcp_f32_e32 v128, v120
	v_rcp_f32_e32 v129, v121
	v_rcp_f32_e32 v130, v122
	v_rcp_f32_e32 v131, v123
	s_nop 1
	v_pk_mul_f32 v[72:73], v[72:73], v[124:125]
	v_pk_mul_f32 v[80:81], v[80:81], v[124:125]
	v_pk_mul_f32 v[88:89], v[88:89], v[64:65]
	v_pk_mul_f32 v[96:97], v[96:97], v[116:117]
	v_pk_mul_f32 v[74:75], v[74:75], v[126:127]
	v_pk_mul_f32 v[82:83], v[82:83], v[126:127]
	v_pk_mul_f32 v[90:91], v[90:91], v[66:67]
	v_pk_mul_f32 v[98:99], v[98:99], v[118:119]
	v_pk_mul_f32 v[76:77], v[76:77], v[128:129]
	v_pk_mul_f32 v[84:85], v[84:85], v[128:129]
	v_pk_mul_f32 v[92:93], v[92:93], v[68:69]
	v_pk_mul_f32 v[100:101], v[100:101], v[120:121]
	v_pk_mul_f32 v[78:79], v[78:79], v[130:131]
	v_pk_mul_f32 v[86:87], v[86:87], v[130:131]
	v_pk_mul_f32 v[94:95], v[94:95], v[70:71]
	v_pk_mul_f32 v[102:103], v[102:103], v[122:123]
	global_load_dwordx2 v[46:47], v5, s[36:37]
	global_load_dwordx2 v[48:49], v5, s[36:37] offset:64
	global_load_dwordx2 v[50:51], v5, s[38:39]
	global_load_dwordx2 v[52:53], v5, s[38:39] offset:64
	global_load_dwordx2 v[54:55], v5, s[40:41]
	global_load_dwordx2 v[56:57], v5, s[40:41] offset:64
	global_load_dwordx2 v[58:59], v5, s[42:43]
	global_load_dwordx2 v[60:61], v5, s[42:43] offset:64
	global_load_dword v62, v6, s[46:47]
	global_load_dword v63, v9, s[44:45]
	v_add_u32_e32 v5, s54, v5
	v_add_u32_e32 v6, s55, v6
	v_add_u32_e32 v9, s54, v9
	ds_write_b32 v159, v161 offset:34816
	ds_write_b128 v8, v[72:75] offset:34816
	s_sleep 1
	ds_write_b128 v8, v[76:79] offset:34944
	ds_write_b128 v8, v[80:83] offset:35072
	s_sleep 1
	ds_write_b128 v8, v[84:87] offset:35200
	ds_write2_b32 v140, v96, v97 offset0:1 offset1:3
	s_sleep 1
	ds_write2_b32 v141, v88, v89 offset0:0 offset1:2
	ds_write2_b32 v140, v98, v99 offset0:65 offset1:67
	s_sleep 1
	ds_write2_b32 v141, v90, v91 offset0:64 offset1:66
	ds_write2_b32 v140, v100, v101 offset0:33 offset1:35
	s_sleep 1
	ds_write2_b32 v141, v92, v93 offset0:32 offset1:34
	ds_write2_b32 v140, v102, v103 offset0:97 offset1:99
	s_sleep 1
	ds_write2_b32 v141, v94, v95 offset0:96 offset1:98
	ds_write2_b32 v143, v104, v105 offset1:36
	s_sleep 1
	s_cmp_lg_u32 s7, 4
	s_cbranch_scc1 .Lsc_nokb2
	s_and_saveexec_b64 s[68:69], s[12:13]
	ds_write_b128 v158, v[88:91] offset:34816
	ds_write_b128 v158, v[92:95] offset:34944
	s_mov_b64 exec, s[68:69]

.Lsc_G_loop:
	s_waitcnt vmcnt(10)
	v_lshlrev_b32_e32 v64, 16, v36
	v_and_b32_e32 v65, 0xffff0000, v36
	v_lshlrev_b32_e32 v66, 16, v37
	v_and_b32_e32 v67, 0xffff0000, v37
	v_lshlrev_b32_e32 v68, 16, v38
	v_and_b32_e32 v69, 0xffff0000, v38
	v_lshlrev_b32_e32 v70, 16, v39
	v_and_b32_e32 v71, 0xffff0000, v39
	ds_write_b128 v153, v[64:67]
	ds_write_b128 v153, v[68:71] offset:128
	s_waitcnt lgkmcnt(0)
	ds_read_b32 v124, v154 offset:0
	ds_read_b32 v125, v154 offset:256
	ds_read_b32 v126, v154 offset:512
	ds_read_b32 v127, v154 offset:768
	ds_read_b32 v128, v154 offset:1024
	ds_read_b32 v129, v154 offset:1280
	ds_read_b32 v130, v154 offset:1536
	ds_read_b32 v131, v154 offset:1792
	v_lshlrev_b32_e32 v108, 16, v32
	v_and_b32_e32 v109, 0xffff0000, v32
	v_lshlrev_b32_e32 v110, 16, v40
	v_and_b32_e32 v111, 0xffff0000, v40
	v_lshlrev_b32_e32 v96, 16, v28
	v_and_b32_e32 v97, 0xffff0000, v28
	v_pk_mul_f32 v[114:115], v[12:13], v[108:109]
	v_pk_fma_f32 v[112:113], v[20:21], v[110:111], v[190:191]
	v_pk_mul_f32 v[88:89], v[44:45], v[114:115] op_sel_hi:[0,1]
	v_pk_mul_f32 v[72:73], v[112:113], v[108:109]
	v_pk_mul_f32 v[80:81], v[88:89], v[110:111]
	v_lshlrev_b32_e32 v108, 16, v33
	v_and_b32_e32 v109, 0xffff0000, v33
	v_lshlrev_b32_e32 v110, 16, v41
	v_and_b32_e32 v111, 0xffff0000, v41
	v_lshlrev_b32_e32 v98, 16, v29
	v_and_b32_e32 v99, 0xffff0000, v29
	v_pk_mul_f32 v[114:115], v[14:15], v[108:109]
	v_pk_fma_f32 v[112:113], v[22:23], v[110:111], v[192:193]
	v_pk_mul_f32 v[90:91], v[44:45], v[114:115] op_sel_hi:[0,1]
	v_pk_mul_f32 v[74:75], v[112:113], v[108:109]
	v_pk_mul_f32 v[82:83], v[90:91], v[110:111]
	v_lshlrev_b32_e32 v108, 16, v34
	v_and_b32_e32 v109, 0xffff0000, v34
	v_lshlrev_b32_e32 v110, 16, v42
	v_and_b32_e32 v111, 0xffff0000, v42
	v_lshlrev_b32_e32 v100, 16, v30
	v_and_b32_e32 v101, 0xffff0000, v30
	v_pk_mul_f32 v[114:115], v[16:17], v[108:109]
	v_pk_fma_f32 v[112:113], v[24:25], v[110:111], v[194:195]
	v_pk_mul_f32 v[92:93], v[44:45], v[114:115] op_sel_hi:[0,1]
	v_pk_mul_f32 v[76:77], v[112:113], v[108:109]
	v_pk_mul_f32 v[84:85], v[92:93], v[110:111]
	v_lshlrev_b32_e32 v108, 16, v35
	v_and_b32_e32 v109, 0xffff0000, v35
	v_lshlrev_b32_e32 v110, 16, v43
	v_and_b32_e32 v111, 0xffff0000, v43
	v_lshlrev_b32_e32 v102, 16, v31
	v_and_b32_e32 v103, 0xffff0000, v31
	v_pk_mul_f32 v[114:115], v[18:19], v[108:109]
	v_pk_fma_f32 v[112:113], v[26:27], v[110:111], v[196:197]
	v_pk_mul_f32 v[94:95], v[44:45], v[114:115] op_sel_hi:[0,1]
	v_pk_mul_f32 v[78:79], v[112:113], v[108:109]
	v_pk_mul_f32 v[86:87], v[94:95], v[110:111]
	v_lshlrev_b32_e32 v104, 16, v45
	v_and_b32_e32 v105, 0xffff0000, v45
	s_waitcnt lgkmcnt(0)
	v_add_f32_e32 v125, v124, v125
	v_add_f32_e32 v126, v125, v126
	v_add_f32_e32 v127, v126, v127
	v_add_f32_e32 v128, v127, v128
	v_add_f32_e32 v129, v128, v129
	v_add_f32_e32 v130, v129, v130
	v_add_f32_e32 v131, v130, v131
	v_mul_f32_e32 v189, 0x3fb8aa3b, v131
	ds_write_b32 v180, v189 offset:0
	v_add_u32_e32 v184, 1, v146
	s_waitcnt lgkmcnt(0)
	ds_write_b32 v162, v184
	s_add_u32 s73, s6, 1
	s_mov_b32 s69, 0x100000

.Lsc_gf_go3:
	ds_read_b32 v185, v174 offset:0
	ds_read_b32 v186, v175 offset:0
	ds_read_b32 v187, v176 offset:0
	s_waitcnt lgkmcnt(0)
	v_add_f32_e32 v185, v185, v186
	v_add_f32_e32 v185, v185, v187
	v_fma_f32 v124, v124, s14, v185
	v_fma_f32 v125, v125, s14, v185
	v_fma_f32 v126, v126, s14, v185
	v_fma_f32 v127, v127, s14, v185
	v_fma_f32 v128, v128, s14, v185
	v_fma_f32 v129, v129, s14, v185
	v_fma_f32 v130, v130, s14, v185
	v_fma_f32 v131, v131, s14, v185
	v_exp_f32_e64 v188, -v185
	v_exp_f32_e64 v124, -v124
	v_exp_f32_e64 v125, -v125
	v_exp_f32_e64 v126, -v126
	v_exp_f32_e64 v127, -v127
	v_exp_f32_e64 v128, -v128
	v_exp_f32_e64 v129, -v129
	v_exp_f32_e64 v130, -v130
	v_exp_f32_e64 v131, -v131
	s_nop 0
	ds_write_b32 v155, v188
	ds_write_b32 v155, v124 offset:256
	ds_write_b32 v155, v125 offset:512
	ds_write_b32 v155, v126 offset:768
	ds_write_b32 v155, v127 offset:1024
	ds_write_b32 v155, v128 offset:1280
	ds_write_b32 v155, v129 offset:1536
	ds_write_b32 v155, v130 offset:1792
	ds_write_b32 v155, v131 offset:2048
	v_mov_b32_e32 v161, v131
	s_waitcnt lgkmcnt(0)
	ds_read_b128 v[64:67], v153 offset:2048
	ds_read_b128 v[68:71], v153 offset:2176
	ds_read_b128 v[116:119], v153 offset:2304
	ds_read_b128 v[120:123], v153 offset:2432
	s_waitcnt lgkmcnt(0)
	v_rcp_f32_e32 v124, v116
	v_rcp_f32_e32 v125, v117
	v_rcp_f32_e32 v126, v118
	v_rcp_f32_e32 v127, v119
	v_rcp_f32_e32 v128, v120
	v_rcp_f32_e32 v129, v121
	v_rcp_f32_e32 v130, v122
	v_rcp_f32_e32 v131, v123
	s_nop 1
	v_pk_mul_f32 v[72:73], v[72:73], v[124:125]
	v_pk_mul_f32 v[80:81], v[80:81], v[124:125]
	v_pk_mul_f32 v[88:89], v[88:89], v[64:65]
	v_pk_mul_f32 v[96:97], v[96:97], v[116:117]
	v_pk_mul_f32 v[74:75], v[74:75], v[126:127]
	v_pk_mul_f32 v[82:83], v[82:83], v[126:127]
	v_pk_mul_f32 v[90:91], v[90:91], v[66:67]
	v_pk_mul_f32 v[98:99], v[98:99], v[118:119]
	v_pk_mul_f32 v[76:77], v[76:77], v[128:129]
	v_pk_mul_f32 v[84:85], v[84:85], v[128:129]
	v_pk_mul_f32 v[92:93], v[92:93], v[68:69]
	v_pk_mul_f32 v[100:101], v[100:101], v[120:121]
	v_pk_mul_f32 v[78:79], v[78:79], v[130:131]
	v_pk_mul_f32 v[86:87], v[86:87], v[130:131]
	v_pk_mul_f32 v[94:95], v[94:95], v[70:71]
	v_pk_mul_f32 v[102:103], v[102:103], v[122:123]
	global_load_dwordx2 v[28:29], v5, s[36:37]
	global_load_dwordx2 v[30:31], v5, s[36:37] offset:64
	global_load_dwordx2 v[32:33], v5, s[38:39]
	global_load_dwordx2 v[34:35], v5, s[38:39] offset:64
	global_load_dwordx2 v[36:37], v5, s[40:41]
	global_load_dwordx2 v[38:39], v5, s[40:41] offset:64
	global_load_dwordx2 v[40:41], v5, s[42:43]
	global_load_dwordx2 v[42:43], v5, s[42:43] offset:64
	global_load_dword v44, v6, s[46:47]
	global_load_dword v45, v9, s[44:45]
	v_add_u32_e32 v5, s54, v5
	v_add_u32_e32 v6, s55, v6
	v_add_u32_e32 v9, s54, v9
	s_sub_u32 s65, s6, 1
	ds_read_b128 v[148:151], v144
	s_waitcnt lgkmcnt(0)
	v_min_u32_e32 v148, v148, v149
	v_min3_u32 v148, v148, v150, v151
	s_nop 1
	v_readfirstlane_b32 s68, v148
	s_cmp_ge_u32 s68, s65
	s_cbranch_scc1 .Lsc_G_gom0
	s_mov_b32 s69, 0x100000

.Lsc_nokb3:
	ds_read_b128 v[106:109], v2 offset:0
	ds_read_b128 v[122:125], v2 offset:16384
	s_sleep 1
	ds_read_b128 v[110:113], v3 offset:0
	ds_read_b128 v[126:129], v3 offset:16384
	s_sleep 1
	ds_read_b128 v[114:117], v4 offset:0
	ds_read_b128 v[130:133], v4 offset:16384
	s_sleep 1
	ds_read_b128 v[118:121], v10 offset:0
	ds_read_b128 v[134:137], v10 offset:16384
	s_sleep 1
	s_waitcnt lgkmcnt(0)
	v_pk_add_f32 v[106:107], v[106:107], v[108:109]
	v_pk_add_f32 v[110:111], v[110:111], v[112:113]
	v_pk_add_f32 v[114:115], v[114:115], v[116:117]
	v_pk_add_f32 v[118:119], v[118:119], v[120:121]
	v_pk_add_f32 v[106:107], v[106:107], v[110:111]
	v_pk_add_f32 v[114:115], v[114:115], v[118:119]
	v_pk_add_f32 v[106:107], v[106:107], v[114:115]
	v_add_f32_e32 v64, v106, v107
	v_pk_add_f32 v[122:123], v[122:123], v[124:125]
	v_pk_add_f32 v[126:127], v[126:127], v[128:129]
	v_pk_add_f32 v[130:131], v[130:131], v[132:133]
	v_pk_add_f32 v[134:135], v[134:135], v[136:137]
	v_pk_add_f32 v[122:123], v[122:123], v[126:127]
	v_pk_add_f32 v[130:131], v[130:131], v[134:135]
	v_pk_add_f32 v[122:123], v[122:123], v[130:131]
	v_add_f32_e32 v65, v122, v123
	global_store_dword v7, v64, s[48:49]
	global_store_dword v165, v65, s[48:49]
	s_add_u32 s48, s48, s64
	s_addc_u32 s49, s49, s50
	s_add_i32 s6, s6, 1
	v_add_u32_e32 v146, 1, v146
	s_waitcnt lgkmcnt(0)
	ds_write_b32 v145, v146
	s_waitcnt vmcnt(10)
	v_lshlrev_b32_e32 v64, 16, v54
	v_and_b32_e32 v65, 0xffff0000, v54
	v_lshlrev_b32_e32 v66, 16, v55
	v_and_b32_e32 v67, 0xffff0000, v55
	v_lshlrev_b32_e32 v68, 16, v56
	v_and_b32_e32 v69, 0xffff0000, v56
	v_lshlrev_b32_e32 v70, 16, v57
	v_and_b32_e32 v71, 0xffff0000, v57
	ds_write_b128 v153, v[64:67]
	ds_write_b128 v153, v[68:71] offset:128
	s_waitcnt lgkmcnt(0)
	ds_read_b32 v124, v154 offset:0
	ds_read_b32 v125, v154 offset:256
	ds_read_b32 v126, v154 offset:512
	ds_read_b32 v127, v154 offset:768
	ds_read_b32 v128, v154 offset:1024
	ds_read_b32 v129, v154 offset:1280
	ds_read_b32 v130, v154 offset:1536
	ds_read_b32 v131, v154 offset:1792
	v_lshlrev_b32_e32 v108, 16, v50
	v_and_b32_e32 v109, 0xffff0000, v50
	v_lshlrev_b32_e32 v110, 16, v58
	v_and_b32_e32 v111, 0xffff0000, v58
	v_lshlrev_b32_e32 v96, 16, v46
	v_and_b32_e32 v97, 0xffff0000, v46
	v_pk_mul_f32 v[114:115], v[12:13], v[108:109]
	v_pk_fma_f32 v[112:113], v[20:21], v[110:111], v[190:191]
	v_pk_mul_f32 v[88:89], v[62:63], v[114:115] op_sel_hi:[0,1]
	v_pk_mul_f32 v[72:73], v[112:113], v[108:109]
	v_pk_mul_f32 v[80:81], v[88:89], v[110:111]
	v_lshlrev_b32_e32 v108, 16, v51
	v_and_b32_e32 v109, 0xffff0000, v51
	v_lshlrev_b32_e32 v110, 16, v59
	v_and_b32_e32 v111, 0xffff0000, v59
	v_lshlrev_b32_e32 v98, 16, v47
	v_and_b32_e32 v99, 0xffff0000, v47
	v_pk_mul_f32 v[114:115], v[14:15], v[108:109]
	v_pk_fma_f32 v[112:113], v[22:23], v[110:111], v[192:193]
	v_pk_mul_f32 v[90:91], v[62:63], v[114:115] op_sel_hi:[0,1]
	v_pk_mul_f32 v[74:75], v[112:113], v[108:109]
	v_pk_mul_f32 v[82:83], v[90:91], v[110:111]
	v_lshlrev_b32_e32 v108, 16, v52
	v_and_b32_e32 v109, 0xffff0000, v52
	v_lshlrev_b32_e32 v110, 16, v60
	v_and_b32_e32 v111, 0xffff0000, v60
	v_lshlrev_b32_e32 v100, 16, v48
	v_and_b32_e32 v101, 0xffff0000, v48
	v_pk_mul_f32 v[114:115], v[16:17], v[108:109]
	v_pk_fma_f32 v[112:113], v[24:25], v[110:111], v[194:195]
	v_pk_mul_f32 v[92:93], v[62:63], v[114:115] op_sel_hi:[0,1]
	v_pk_mul_f32 v[76:77], v[112:113], v[108:109]
	v_pk_mul_f32 v[84:85], v[92:93], v[110:111]
	v_lshlrev_b32_e32 v108, 16, v53
	v_and_b32_e32 v109, 0xffff0000, v53
	v_lshlrev_b32_e32 v110, 16, v61
	v_and_b32_e32 v111, 0xffff0000, v61
	v_lshlrev_b32_e32 v102, 16, v49
	v_and_b32_e32 v103, 0xffff0000, v49
	v_pk_mul_f32 v[114:115], v[18:19], v[108:109]
	v_pk_fma_f32 v[112:113], v[26:27], v[110:111], v[196:197]
	v_pk_mul_f32 v[94:95], v[62:63], v[114:115] op_sel_hi:[0,1]
	v_pk_mul_f32 v[78:79], v[112:113], v[108:109]
	v_pk_mul_f32 v[86:87], v[94:95], v[110:111]
	v_lshlrev_b32_e32 v104, 16, v63
	v_and_b32_e32 v105, 0xffff0000, v63
	s_waitcnt lgkmcnt(0)
	v_add_f32_e32 v125, v124, v125
	v_add_f32_e32 v126, v125, v126
	v_add_f32_e32 v127, v126, v127
	v_add_f32_e32 v128, v127, v128
	v_add_f32_e32 v129, v128, v129
	v_add_f32_e32 v130, v129, v130
	v_add_f32_e32 v131, v130, v131
	v_mul_f32_e32 v189, 0x3fb8aa3b, v131
	ds_write_b32 v180, v189 offset:1024
	v_add_u32_e32 v184, 1, v146
	s_waitcnt lgkmcnt(0)
	ds_write_b32 v162, v184
	s_add_u32 s73, s6, 1
	s_mov_b32 s69, 0x100000

.Lsc_gf_go4:
	ds_read_b32 v185, v174 offset:1024
	ds_read_b32 v186, v175 offset:1024
	ds_read_b32 v187, v176 offset:1024
	s_waitcnt lgkmcnt(0)
	v_add_f32_e32 v185, v185, v186
	v_add_f32_e32 v185, v185, v187
	v_fma_f32 v124, v124, s14, v185
	v_fma_f32 v125, v125, s14, v185
	v_fma_f32 v126, v126, s14, v185
	v_fma_f32 v127, v127, s14, v185
	v_fma_f32 v128, v128, s14, v185
	v_fma_f32 v129, v129, s14, v185
	v_fma_f32 v130, v130, s14, v185
	v_fma_f32 v131, v131, s14, v185
	v_exp_f32_e64 v188, -v185
	v_exp_f32_e64 v124, -v124
	v_exp_f32_e64 v125, -v125
	v_exp_f32_e64 v126, -v126
	v_exp_f32_e64 v127, -v127
	v_exp_f32_e64 v128, -v128
	v_exp_f32_e64 v129, -v129
	v_exp_f32_e64 v130, -v130
	v_exp_f32_e64 v131, -v131
	s_nop 0
	ds_write_b32 v155, v188
	ds_write_b32 v155, v124 offset:256
	ds_write_b32 v155, v125 offset:512
	ds_write_b32 v155, v126 offset:768
	ds_write_b32 v155, v127 offset:1024
	ds_write_b32 v155, v128 offset:1280
	ds_write_b32 v155, v129 offset:1536
	ds_write_b32 v155, v130 offset:1792
	ds_write_b32 v155, v131 offset:2048
	v_mov_b32_e32 v161, v131
	s_waitcnt lgkmcnt(0)
	ds_read_b128 v[64:67], v153 offset:2048
	ds_read_b128 v[68:71], v153 offset:2176
	ds_read_b128 v[116:119], v153 offset:2304
	ds_read_b128 v[120:123], v153 offset:2432
	s_waitcnt lgkmcnt(0)
	v_rcp_f32_e32 v124, v116
	v_rcp_f32_e32 v125, v117
	v_rcp_f32_e32 v126, v118
	v_rcp_f32_e32 v127, v119
	v_rcp_f32_e32 v128, v120
	v_rcp_f32_e32 v129, v121
	v_rcp_f32_e32 v130, v122
	v_rcp_f32_e32 v131, v123
	s_nop 1
	v_pk_mul_f32 v[72:73], v[72:73], v[124:125]
	v_pk_mul_f32 v[80:81], v[80:81], v[124:125]
	v_pk_mul_f32 v[88:89], v[88:89], v[64:65]
	v_pk_mul_f32 v[96:97], v[96:97], v[116:117]
	v_pk_mul_f32 v[74:75], v[74:75], v[126:127]
	v_pk_mul_f32 v[82:83], v[82:83], v[126:127]
	v_pk_mul_f32 v[90:91], v[90:91], v[66:67]
	v_pk_mul_f32 v[98:99], v[98:99], v[118:119]
	v_pk_mul_f32 v[76:77], v[76:77], v[128:129]
	v_pk_mul_f32 v[84:85], v[84:85], v[128:129]
	v_pk_mul_f32 v[92:93], v[92:93], v[68:69]
	v_pk_mul_f32 v[100:101], v[100:101], v[120:121]
	v_pk_mul_f32 v[78:79], v[78:79], v[130:131]
	v_pk_mul_f32 v[86:87], v[86:87], v[130:131]
	v_pk_mul_f32 v[94:95], v[94:95], v[70:71]
	v_pk_mul_f32 v[102:103], v[102:103], v[122:123]
	global_load_dwordx2 v[46:47], v5, s[36:37]
	global_load_dwordx2 v[48:49], v5, s[36:37] offset:64
	global_load_dwordx2 v[50:51], v5, s[38:39]
	global_load_dwordx2 v[52:53], v5, s[38:39] offset:64
	global_load_dwordx2 v[54:55], v5, s[40:41]
	global_load_dwordx2 v[56:57], v5, s[40:41] offset:64
	global_load_dwordx2 v[58:59], v5, s[42:43]
	global_load_dwordx2 v[60:61], v5, s[42:43] offset:64
	global_load_dword v62, v6, s[46:47]
	global_load_dword v63, v9, s[44:45]
	v_add_u32_e32 v5, s54, v5
	v_add_u32_e32 v6, s55, v6
	v_add_u32_e32 v9, s54, v9
	s_sub_u32 s65, s6, 1
	ds_read_b128 v[148:151], v144
	s_waitcnt lgkmcnt(0)
	v_min_u32_e32 v148, v148, v149
	v_min3_u32 v148, v148, v150, v151
	s_nop 1
	v_readfirstlane_b32 s68, v148
	s_cmp_ge_u32 s68, s65
	s_cbranch_scc1 .Lsc_G_gom1
	s_mov_b32 s69, 0x100000

.Lsc_nokb4:
	ds_read_b128 v[106:109], v2 offset:32768
	ds_read_b128 v[122:125], v2 offset:49152
	s_sleep 1
	ds_read_b128 v[110:113], v3 offset:32768
	ds_read_b128 v[126:129], v3 offset:49152
	s_sleep 1
	ds_read_b128 v[114:117], v4 offset:32768
	ds_read_b128 v[130:133], v4 offset:49152
	s_sleep 1
	ds_read_b128 v[118:121], v10 offset:32768
	ds_read_b128 v[134:137], v10 offset:49152
	s_sleep 1
	s_waitcnt lgkmcnt(0)
	v_pk_add_f32 v[106:107], v[106:107], v[108:109]
	v_pk_add_f32 v[110:111], v[110:111], v[112:113]
	v_pk_add_f32 v[114:115], v[114:115], v[116:117]
	v_pk_add_f32 v[118:119], v[118:119], v[120:121]
	v_pk_add_f32 v[106:107], v[106:107], v[110:111]
	v_pk_add_f32 v[114:115], v[114:115], v[118:119]
	v_pk_add_f32 v[106:107], v[106:107], v[114:115]
	v_add_f32_e32 v64, v106, v107
	v_pk_add_f32 v[122:123], v[122:123], v[124:125]
	v_pk_add_f32 v[126:127], v[126:127], v[128:129]
	v_pk_add_f32 v[130:131], v[130:131], v[132:133]
	v_pk_add_f32 v[134:135], v[134:135], v[136:137]
	v_pk_add_f32 v[122:123], v[122:123], v[126:127]
	v_pk_add_f32 v[130:131], v[130:131], v[134:135]
	v_pk_add_f32 v[122:123], v[122:123], v[130:131]
	v_add_f32_e32 v65, v122, v123
	global_store_dword v7, v64, s[48:49]
	global_store_dword v165, v65, s[48:49]
	s_add_u32 s48, s48, s64
	s_addc_u32 s49, s49, s50
	s_add_i32 s6, s6, 1
	v_add_u32_e32 v146, 1, v146
	s_waitcnt lgkmcnt(0)
	ds_write_b32 v145, v146
	s_cmp_lt_u32 s6, 0xfe
	s_cbranch_scc1 .Lsc_G_loop
	s_waitcnt vmcnt(10)
	v_lshlrev_b32_e32 v64, 16, v36
	v_and_b32_e32 v65, 0xffff0000, v36
	v_lshlrev_b32_e32 v66, 16, v37
	v_and_b32_e32 v67, 0xffff0000, v37
	v_lshlrev_b32_e32 v68, 16, v38
	v_and_b32_e32 v69, 0xffff0000, v38
	v_lshlrev_b32_e32 v70, 16, v39
	v_and_b32_e32 v71, 0xffff0000, v39
	ds_write_b128 v153, v[64:67]
	ds_write_b128 v153, v[68:71] offset:128
	s_waitcnt lgkmcnt(0)
	ds_read_b32 v124, v154 offset:0
	ds_read_b32 v125, v154 offset:256
	ds_read_b32 v126, v154 offset:512
	ds_read_b32 v127, v154 offset:768
	ds_read_b32 v128, v154 offset:1024
	ds_read_b32 v129, v154 offset:1280
	ds_read_b32 v130, v154 offset:1536
	ds_read_b32 v131, v154 offset:1792
	v_lshlrev_b32_e32 v108, 16, v32
	v_and_b32_e32 v109, 0xffff0000, v32
	v_lshlrev_b32_e32 v110, 16, v40
	v_and_b32_e32 v111, 0xffff0000, v40
	v_lshlrev_b32_e32 v96, 16, v28
	v_and_b32_e32 v97, 0xffff0000, v28
	v_pk_mul_f32 v[114:115], v[12:13], v[108:109]
	v_pk_fma_f32 v[112:113], v[20:21], v[110:111], v[190:191]
	v_pk_mul_f32 v[88:89], v[44:45], v[114:115] op_sel_hi:[0,1]
	v_pk_mul_f32 v[72:73], v[112:113], v[108:109]
	v_pk_mul_f32 v[80:81], v[88:89], v[110:111]
	v_lshlrev_b32_e32 v108, 16, v33
	v_and_b32_e32 v109, 0xffff0000, v33
	v_lshlrev_b32_e32 v110, 16, v41
	v_and_b32_e32 v111, 0xffff0000, v41
	v_lshlrev_b32_e32 v98, 16, v29
	v_and_b32_e32 v99, 0xffff0000, v29
	v_pk_mul_f32 v[114:115], v[14:15], v[108:109]
	v_pk_fma_f32 v[112:113], v[22:23], v[110:111], v[192:193]
	v_pk_mul_f32 v[90:91], v[44:45], v[114:115] op_sel_hi:[0,1]
	v_pk_mul_f32 v[74:75], v[112:113], v[108:109]
	v_pk_mul_f32 v[82:83], v[90:91], v[110:111]
	v_lshlrev_b32_e32 v108, 16, v34
	v_and_b32_e32 v109, 0xffff0000, v34
	v_lshlrev_b32_e32 v110, 16, v42
	v_and_b32_e32 v111, 0xffff0000, v42
	v_lshlrev_b32_e32 v100, 16, v30
	v_and_b32_e32 v101, 0xffff0000, v30
	v_pk_mul_f32 v[114:115], v[16:17], v[108:109]
	v_pk_fma_f32 v[112:113], v[24:25], v[110:111], v[194:195]
	v_pk_mul_f32 v[92:93], v[44:45], v[114:115] op_sel_hi:[0,1]
	v_pk_mul_f32 v[76:77], v[112:113], v[108:109]
	v_pk_mul_f32 v[84:85], v[92:93], v[110:111]
	v_lshlrev_b32_e32 v108, 16, v35
	v_and_b32_e32 v109, 0xffff0000, v35
	v_lshlrev_b32_e32 v110, 16, v43
	v_and_b32_e32 v111, 0xffff0000, v43
	v_lshlrev_b32_e32 v102, 16, v31
	v_and_b32_e32 v103, 0xffff0000, v31
	v_pk_mul_f32 v[114:115], v[18:19], v[108:109]
	v_pk_fma_f32 v[112:113], v[26:27], v[110:111], v[196:197]
	v_pk_mul_f32 v[94:95], v[44:45], v[114:115] op_sel_hi:[0,1]
	v_pk_mul_f32 v[78:79], v[112:113], v[108:109]
	v_pk_mul_f32 v[86:87], v[94:95], v[110:111]
	v_lshlrev_b32_e32 v104, 16, v45
	v_and_b32_e32 v105, 0xffff0000, v45
	s_waitcnt lgkmcnt(0)
	v_add_f32_e32 v125, v124, v125
	v_add_f32_e32 v126, v125, v126
	v_add_f32_e32 v127, v126, v127
	v_add_f32_e32 v128, v127, v128
	v_add_f32_e32 v129, v128, v129
	v_add_f32_e32 v130, v129, v130
	v_add_f32_e32 v131, v130, v131
	v_mul_f32_e32 v189, 0x3fb8aa3b, v131
	ds_write_b32 v180, v189 offset:0
	v_add_u32_e32 v184, 1, v146
	s_waitcnt lgkmcnt(0)
	ds_write_b32 v162, v184
	s_add_u32 s73, s6, 1
	s_mov_b32 s69, 0x100000

.Lsc_gf_go5:
	ds_read_b32 v185, v174 offset:0
	ds_read_b32 v186, v175 offset:0
	ds_read_b32 v187, v176 offset:0
	s_waitcnt lgkmcnt(0)
	v_add_f32_e32 v185, v185, v186
	v_add_f32_e32 v185, v185, v187
	v_fma_f32 v124, v124, s14, v185
	v_fma_f32 v125, v125, s14, v185
	v_fma_f32 v126, v126, s14, v185
	v_fma_f32 v127, v127, s14, v185
	v_fma_f32 v128, v128, s14, v185
	v_fma_f32 v129, v129, s14, v185
	v_fma_f32 v130, v130, s14, v185
	v_fma_f32 v131, v131, s14, v185
	v_exp_f32_e64 v188, -v185
	v_exp_f32_e64 v124, -v124
	v_exp_f32_e64 v125, -v125
	v_exp_f32_e64 v126, -v126
	v_exp_f32_e64 v127, -v127
	v_exp_f32_e64 v128, -v128
	v_exp_f32_e64 v129, -v129
	v_exp_f32_e64 v130, -v130
	v_exp_f32_e64 v131, -v131
	s_nop 0
	ds_write_b32 v155, v188
	ds_write_b32 v155, v124 offset:256
	ds_write_b32 v155, v125 offset:512
	ds_write_b32 v155, v126 offset:768
	ds_write_b32 v155, v127 offset:1024
	ds_write_b32 v155, v128 offset:1280
	ds_write_b32 v155, v129 offset:1536
	ds_write_b32 v155, v130 offset:1792
	ds_write_b32 v155, v131 offset:2048
	v_mov_b32_e32 v161, v131
	s_waitcnt lgkmcnt(0)
	ds_read_b128 v[64:67], v153 offset:2048
	ds_read_b128 v[68:71], v153 offset:2176
	ds_read_b128 v[116:119], v153 offset:2304
	ds_read_b128 v[120:123], v153 offset:2432
	s_waitcnt lgkmcnt(0)
	v_rcp_f32_e32 v124, v116
	v_rcp_f32_e32 v125, v117
	v_rcp_f32_e32 v126, v118
	v_rcp_f32_e32 v127, v119
	v_rcp_f32_e32 v128, v120
	v_rcp_f32_e32 v129, v121
	v_rcp_f32_e32 v130, v122
	v_rcp_f32_e32 v131, v123
	s_nop 1
	v_pk_mul_f32 v[72:73], v[72:73], v[124:125]
	v_pk_mul_f32 v[80:81], v[80:81], v[124:125]
	v_pk_mul_f32 v[88:89], v[88:89], v[64:65]
	v_pk_mul_f32 v[96:97], v[96:97], v[116:117]
	v_pk_mul_f32 v[74:75], v[74:75], v[126:127]
	v_pk_mul_f32 v[82:83], v[82:83], v[126:127]
	v_pk_mul_f32 v[90:91], v[90:91], v[66:67]
	v_pk_mul_f32 v[98:99], v[98:99], v[118:119]
	v_pk_mul_f32 v[76:77], v[76:77], v[128:129]
	v_pk_mul_f32 v[84:85], v[84:85], v[128:129]
	v_pk_mul_f32 v[92:93], v[92:93], v[68:69]
	v_pk_mul_f32 v[100:101], v[100:101], v[120:121]
	v_pk_mul_f32 v[78:79], v[78:79], v[130:131]
	v_pk_mul_f32 v[86:87], v[86:87], v[130:131]
	v_pk_mul_f32 v[94:95], v[94:95], v[70:71]
	v_pk_mul_f32 v[102:103], v[102:103], v[122:123]
	s_sub_u32 s65, s6, 1
	ds_read_b128 v[148:151], v144
	s_waitcnt lgkmcnt(0)
	v_min_u32_e32 v148, v148, v149
	v_min3_u32 v148, v148, v150, v151
	s_nop 1
	v_readfirstlane_b32 s68, v148
	s_cmp_ge_u32 s68, s65
	s_cbranch_scc1 .Lsc_G_goz0
	s_mov_b32 s69, 0x100000

.Lsc_nokb5:
	ds_read_b128 v[106:109], v2 offset:0
	ds_read_b128 v[122:125], v2 offset:16384
	s_sleep 1
	ds_read_b128 v[110:113], v3 offset:0
	ds_read_b128 v[126:129], v3 offset:16384
	s_sleep 1
	ds_read_b128 v[114:117], v4 offset:0
	ds_read_b128 v[130:133], v4 offset:16384
	s_sleep 1
	ds_read_b128 v[118:121], v10 offset:0
	ds_read_b128 v[134:137], v10 offset:16384
	s_sleep 1
	s_waitcnt lgkmcnt(0)
	v_pk_add_f32 v[106:107], v[106:107], v[108:109]
	v_pk_add_f32 v[110:111], v[110:111], v[112:113]
	v_pk_add_f32 v[114:115], v[114:115], v[116:117]
	v_pk_add_f32 v[118:119], v[118:119], v[120:121]
	v_pk_add_f32 v[106:107], v[106:107], v[110:111]
	v_pk_add_f32 v[114:115], v[114:115], v[118:119]
	v_pk_add_f32 v[106:107], v[106:107], v[114:115]
	v_add_f32_e32 v64, v106, v107
	v_pk_add_f32 v[122:123], v[122:123], v[124:125]
	v_pk_add_f32 v[126:127], v[126:127], v[128:129]
	v_pk_add_f32 v[130:131], v[130:131], v[132:133]
	v_pk_add_f32 v[134:135], v[134:135], v[136:137]
	v_pk_add_f32 v[122:123], v[122:123], v[126:127]
	v_pk_add_f32 v[130:131], v[130:131], v[134:135]
	v_pk_add_f32 v[122:123], v[122:123], v[130:131]
	v_add_f32_e32 v65, v122, v123
	global_store_dword v7, v64, s[48:49]
	global_store_dword v165, v65, s[48:49]
	s_add_u32 s48, s48, s64
	s_addc_u32 s49, s49, s50
	s_add_i32 s6, s6, 1
	v_add_u32_e32 v146, 1, v146
	s_waitcnt lgkmcnt(0)
	ds_write_b32 v145, v146
	s_waitcnt vmcnt(0)
	v_lshlrev_b32_e32 v64, 16, v54
	v_and_b32_e32 v65, 0xffff0000, v54
	v_lshlrev_b32_e32 v66, 16, v55
	v_and_b32_e32 v67, 0xffff0000, v55
	v_lshlrev_b32_e32 v68, 16, v56
	v_and_b32_e32 v69, 0xffff0000, v56
	v_lshlrev_b32_e32 v70, 16, v57
	v_and_b32_e32 v71, 0xffff0000, v57
	ds_write_b128 v153, v[64:67]
	ds_write_b128 v153, v[68:71] offset:128
	s_waitcnt lgkmcnt(0)
	ds_read_b32 v124, v154 offset:0
	ds_read_b32 v125, v154 offset:256
	ds_read_b32 v126, v154 offset:512
	ds_read_b32 v127, v154 offset:768
	ds_read_b32 v128, v154 offset:1024
	ds_read_b32 v129, v154 offset:1280
	ds_read_b32 v130, v154 offset:1536
	ds_read_b32 v131, v154 offset:1792
	v_lshlrev_b32_e32 v108, 16, v50
	v_and_b32_e32 v109, 0xffff0000, v50
	v_lshlrev_b32_e32 v110, 16, v58
	v_and_b32_e32 v111, 0xffff0000, v58
	v_lshlrev_b32_e32 v96, 16, v46
	v_and_b32_e32 v97, 0xffff0000, v46
	v_pk_mul_f32 v[114:115], v[12:13], v[108:109]
	v_pk_fma_f32 v[112:113], v[20:21], v[110:111], v[190:191]
	v_pk_mul_f32 v[88:89], v[62:63], v[114:115] op_sel_hi:[0,1]
	v_pk_mul_f32 v[72:73], v[112:113], v[108:109]
	v_pk_mul_f32 v[80:81], v[88:89], v[110:111]
	v_lshlrev_b32_e32 v108, 16, v51
	v_and_b32_e32 v109, 0xffff0000, v51
	v_lshlrev_b32_e32 v110, 16, v59
	v_and_b32_e32 v111, 0xffff0000, v59
	v_lshlrev_b32_e32 v98, 16, v47
	v_and_b32_e32 v99, 0xffff0000, v47
	v_pk_mul_f32 v[114:115], v[14:15], v[108:109]
	v_pk_fma_f32 v[112:113], v[22:23], v[110:111], v[192:193]
	v_pk_mul_f32 v[90:91], v[62:63], v[114:115] op_sel_hi:[0,1]
	v_pk_mul_f32 v[74:75], v[112:113], v[108:109]
	v_pk_mul_f32 v[82:83], v[90:91], v[110:111]
	v_lshlrev_b32_e32 v108, 16, v52
	v_and_b32_e32 v109, 0xffff0000, v52
	v_lshlrev_b32_e32 v110, 16, v60
	v_and_b32_e32 v111, 0xffff0000, v60
	v_lshlrev_b32_e32 v100, 16, v48
	v_and_b32_e32 v101, 0xffff0000, v48
	v_pk_mul_f32 v[114:115], v[16:17], v[108:109]
	v_pk_fma_f32 v[112:113], v[24:25], v[110:111], v[194:195]
	v_pk_mul_f32 v[92:93], v[62:63], v[114:115] op_sel_hi:[0,1]
	v_pk_mul_f32 v[76:77], v[112:113], v[108:109]
	v_pk_mul_f32 v[84:85], v[92:93], v[110:111]
	v_lshlrev_b32_e32 v108, 16, v53
	v_and_b32_e32 v109, 0xffff0000, v53
	v_lshlrev_b32_e32 v110, 16, v61
	v_and_b32_e32 v111, 0xffff0000, v61
	v_lshlrev_b32_e32 v102, 16, v49
	v_and_b32_e32 v103, 0xffff0000, v49
	v_pk_mul_f32 v[114:115], v[18:19], v[108:109]
	v_pk_fma_f32 v[112:113], v[26:27], v[110:111], v[196:197]
	v_pk_mul_f32 v[94:95], v[62:63], v[114:115] op_sel_hi:[0,1]
	v_pk_mul_f32 v[78:79], v[112:113], v[108:109]
	v_pk_mul_f32 v[86:87], v[94:95], v[110:111]
	v_lshlrev_b32_e32 v104, 16, v63
	v_and_b32_e32 v105, 0xffff0000, v63
	s_waitcnt lgkmcnt(0)
	v_add_f32_e32 v125, v124, v125
	v_add_f32_e32 v126, v125, v126
	v_add_f32_e32 v127, v126, v127
	v_add_f32_e32 v128, v127, v128
	v_add_f32_e32 v129, v128, v129
	v_add_f32_e32 v130, v129, v130
	v_add_f32_e32 v131, v130, v131
	v_mul_f32_e32 v189, 0x3fb8aa3b, v131
	ds_write_b32 v180, v189 offset:1024
	v_add_u32_e32 v184, 1, v146
	s_waitcnt lgkmcnt(0)
	ds_write_b32 v162, v184
	s_add_u32 s73, s6, 1
	s_mov_b32 s69, 0x100000

.Lsc_gf_go6:
	ds_read_b32 v185, v174 offset:1024
	ds_read_b32 v186, v175 offset:1024
	ds_read_b32 v187, v176 offset:1024
	s_waitcnt lgkmcnt(0)
	v_add_f32_e32 v185, v185, v186
	v_add_f32_e32 v185, v185, v187
	v_fma_f32 v124, v124, s14, v185
	v_fma_f32 v125, v125, s14, v185
	v_fma_f32 v126, v126, s14, v185
	v_fma_f32 v127, v127, s14, v185
	v_fma_f32 v128, v128, s14, v185
	v_fma_f32 v129, v129, s14, v185
	v_fma_f32 v130, v130, s14, v185
	v_fma_f32 v131, v131, s14, v185
	v_exp_f32_e64 v188, -v185
	v_exp_f32_e64 v124, -v124
	v_exp_f32_e64 v125, -v125
	v_exp_f32_e64 v126, -v126
	v_exp_f32_e64 v127, -v127
	v_exp_f32_e64 v128, -v128
	v_exp_f32_e64 v129, -v129
	v_exp_f32_e64 v130, -v130
	v_exp_f32_e64 v131, -v131
	s_nop 0
	ds_write_b32 v155, v188
	ds_write_b32 v155, v124 offset:256
	ds_write_b32 v155, v125 offset:512
	ds_write_b32 v155, v126 offset:768
	ds_write_b32 v155, v127 offset:1024
	ds_write_b32 v155, v128 offset:1280
	ds_write_b32 v155, v129 offset:1536
	ds_write_b32 v155, v130 offset:1792
	ds_write_b32 v155, v131 offset:2048
	v_mov_b32_e32 v161, v131
	s_waitcnt lgkmcnt(0)
	ds_read_b128 v[64:67], v153 offset:2048
	ds_read_b128 v[68:71], v153 offset:2176
	ds_read_b128 v[116:119], v153 offset:2304
	ds_read_b128 v[120:123], v153 offset:2432
	s_waitcnt lgkmcnt(0)
	v_rcp_f32_e32 v124, v116
	v_rcp_f32_e32 v125, v117
	v_rcp_f32_e32 v126, v118
	v_rcp_f32_e32 v127, v119
	v_rcp_f32_e32 v128, v120
	v_rcp_f32_e32 v129, v121
	v_rcp_f32_e32 v130, v122
	v_rcp_f32_e32 v131, v123
	s_nop 1
	v_pk_mul_f32 v[72:73], v[72:73], v[124:125]
	v_pk_mul_f32 v[80:81], v[80:81], v[124:125]
	v_pk_mul_f32 v[88:89], v[88:89], v[64:65]
	v_pk_mul_f32 v[96:97], v[96:97], v[116:117]
	v_pk_mul_f32 v[74:75], v[74:75], v[126:127]
	v_pk_mul_f32 v[82:83], v[82:83], v[126:127]
	v_pk_mul_f32 v[90:91], v[90:91], v[66:67]
	v_pk_mul_f32 v[98:99], v[98:99], v[118:119]
	v_pk_mul_f32 v[76:77], v[76:77], v[128:129]
	v_pk_mul_f32 v[84:85], v[84:85], v[128:129]
	v_pk_mul_f32 v[92:93], v[92:93], v[68:69]
	v_pk_mul_f32 v[100:101], v[100:101], v[120:121]
	v_pk_mul_f32 v[78:79], v[78:79], v[130:131]
	v_pk_mul_f32 v[86:87], v[86:87], v[130:131]
	v_pk_mul_f32 v[94:95], v[94:95], v[70:71]
	v_pk_mul_f32 v[102:103], v[102:103], v[122:123]
	s_sub_u32 s65, s6, 1
	ds_read_b128 v[148:151], v144
	s_waitcnt lgkmcnt(0)
	v_min_u32_e32 v148, v148, v149
	v_min3_u32 v148, v148, v150, v151
	s_nop 1
	v_readfirstlane_b32 s68, v148
	s_cmp_ge_u32 s68, s65
	s_cbranch_scc1 .Lsc_G_goz1
	s_mov_b32 s69, 0x100000

.Lsc_nokb6:
	ds_read_b128 v[106:109], v2 offset:32768
	ds_read_b128 v[122:125], v2 offset:49152
	s_sleep 1
	ds_read_b128 v[110:113], v3 offset:32768
	ds_read_b128 v[126:129], v3 offset:49152
	s_sleep 1
	ds_read_b128 v[114:117], v4 offset:32768
	ds_read_b128 v[130:133], v4 offset:49152
	s_sleep 1
	ds_read_b128 v[118:121], v10 offset:32768
	ds_read_b128 v[134:137], v10 offset:49152
	s_sleep 1
	s_waitcnt lgkmcnt(0)
	v_pk_add_f32 v[106:107], v[106:107], v[108:109]
	v_pk_add_f32 v[110:111], v[110:111], v[112:113]
	v_pk_add_f32 v[114:115], v[114:115], v[116:117]
	v_pk_add_f32 v[118:119], v[118:119], v[120:121]
	v_pk_add_f32 v[106:107], v[106:107], v[110:111]
	v_pk_add_f32 v[114:115], v[114:115], v[118:119]
	v_pk_add_f32 v[106:107], v[106:107], v[114:115]
	v_add_f32_e32 v64, v106, v107
	v_pk_add_f32 v[122:123], v[122:123], v[124:125]
	v_pk_add_f32 v[126:127], v[126:127], v[128:129]
	v_pk_add_f32 v[130:131], v[130:131], v[132:133]
	v_pk_add_f32 v[134:135], v[134:135], v[136:137]
	v_pk_add_f32 v[122:123], v[122:123], v[126:127]
	v_pk_add_f32 v[130:131], v[130:131], v[134:135]
	v_pk_add_f32 v[122:123], v[122:123], v[130:131]
	v_add_f32_e32 v65, v122, v123
	global_store_dword v7, v64, s[48:49]
	global_store_dword v165, v65, s[48:49]
	s_add_u32 s48, s48, s64
	s_addc_u32 s49, s49, s50
	s_add_i32 s6, s6, 1
	v_add_u32_e32 v146, 1, v146
	s_waitcnt lgkmcnt(0)
	ds_write_b32 v145, v146
	s_sub_u32 s65, s6, 1
	ds_read_b128 v[148:151], v144
	s_waitcnt lgkmcnt(0)
	v_min_u32_e32 v148, v148, v149
	v_min3_u32 v148, v148, v150, v151
	s_nop 1
	v_readfirstlane_b32 s68, v148
	s_cmp_ge_u32 s68, s65
	s_cbranch_scc1 .Lsc_G_goz2
	s_mov_b32 s69, 0x100000

.Lsc_G_goz2:
	ds_read_b128 v[106:109], v2 offset:0
	ds_read_b128 v[122:125], v2 offset:16384
	s_sleep 1
	ds_read_b128 v[110:113], v3 offset:0
	ds_read_b128 v[126:129], v3 offset:16384
	s_sleep 1
	ds_read_b128 v[114:117], v4 offset:0
	ds_read_b128 v[130:133], v4 offset:16384
	s_sleep 1
	ds_read_b128 v[118:121], v10 offset:0
	ds_read_b128 v[134:137], v10 offset:16384
	s_sleep 1
	s_waitcnt lgkmcnt(0)
	v_pk_add_f32 v[106:107], v[106:107], v[108:109]
	v_pk_add_f32 v[110:111], v[110:111], v[112:113]
	v_pk_add_f32 v[114:115], v[114:115], v[116:117]
	v_pk_add_f32 v[118:119], v[118:119], v[120:121]
	v_pk_add_f32 v[106:107], v[106:107], v[110:111]
	v_pk_add_f32 v[114:115], v[114:115], v[118:119]
	v_pk_add_f32 v[106:107], v[106:107], v[114:115]
	v_add_f32_e32 v64, v106, v107
	v_pk_add_f32 v[122:123], v[122:123], v[124:125]
	v_pk_add_f32 v[126:127], v[126:127], v[128:129]
	v_pk_add_f32 v[130:131], v[130:131], v[132:133]
	v_pk_add_f32 v[134:135], v[134:135], v[136:137]
	v_pk_add_f32 v[122:123], v[122:123], v[126:127]
	v_pk_add_f32 v[130:131], v[130:131], v[134:135]
	v_pk_add_f32 v[122:123], v[122:123], v[130:131]
	v_add_f32_e32 v65, v122, v123
	global_store_dword v7, v64, s[48:49]
	global_store_dword v165, v65, s[48:49]
	s_add_u32 s48, s48, s64
	s_addc_u32 s49, s49, s50
	s_add_i32 s6, s6, 1
	v_add_u32_e32 v146, 1, v146
	s_waitcnt lgkmcnt(0)
	ds_write_b32 v145, v146
	s_sub_u32 s65, s6, 1
	ds_read_b128 v[148:151], v144
	s_waitcnt lgkmcnt(0)
	v_min_u32_e32 v148, v148, v149
	v_min3_u32 v148, v148, v150, v151
	s_nop 1
	v_readfirstlane_b32 s68, v148
	s_cmp_ge_u32 s68, s65
	s_cbranch_scc1 .Lsc_G_goz3
	s_mov_b32 s69, 0x100000

.Lsc_G_goz3:
	ds_read_b128 v[106:109], v2 offset:32768
	ds_read_b128 v[122:125], v2 offset:49152
	s_sleep 1
	ds_read_b128 v[110:113], v3 offset:32768
	ds_read_b128 v[126:129], v3 offset:49152
	s_sleep 1
	ds_read_b128 v[114:117], v4 offset:32768
	ds_read_b128 v[130:133], v4 offset:49152
	s_sleep 1
	ds_read_b128 v[118:121], v10 offset:32768
	ds_read_b128 v[134:137], v10 offset:49152
	s_sleep 1
	s_waitcnt lgkmcnt(0)
	v_pk_add_f32 v[106:107], v[106:107], v[108:109]
	v_pk_add_f32 v[110:111], v[110:111], v[112:113]
	v_pk_add_f32 v[114:115], v[114:115], v[116:117]
	v_pk_add_f32 v[118:119], v[118:119], v[120:121]
	v_pk_add_f32 v[106:107], v[106:107], v[110:111]
	v_pk_add_f32 v[114:115], v[114:115], v[118:119]
	v_pk_add_f32 v[106:107], v[106:107], v[114:115]
	v_add_f32_e32 v64, v106, v107
	v_pk_add_f32 v[122:123], v[122:123], v[124:125]
	v_pk_add_f32 v[126:127], v[126:127], v[128:129]
	v_pk_add_f32 v[130:131], v[130:131], v[132:133]
	v_pk_add_f32 v[134:135], v[134:135], v[136:137]
	v_pk_add_f32 v[122:123], v[122:123], v[126:127]
	v_pk_add_f32 v[130:131], v[130:131], v[134:135]
	v_pk_add_f32 v[122:123], v[122:123], v[130:131]
	v_add_f32_e32 v65, v122, v123
	global_store_dword v7, v64, s[48:49]
	global_store_dword v165, v65, s[48:49]
	s_add_u32 s48, s48, s64
	s_addc_u32 s49, s49, s50
	s_add_i32 s6, s6, 1
	v_add_u32_e32 v146, 1, v146
	s_waitcnt lgkmcnt(0)
	ds_write_b32 v145, v146
